# in-proj GEMM K-loop: LDS-DMA loads use SGPR base + 32-bit VGPR offset (16 fewer 64-bit VALU adds per iteration)
# baseline (speedup 1.0000x reference)
; #define PG8_STAGE(bufoff, gbase, voff) do { _Pragma("unroll") for (int _i = 0; _i < 2; ++_i) \
;         __builtin_amdgcn_global_load_lds((const unsigned*)((const char*)(gbase) + (voff)[_i]), (PG8_LAS unsigned*)(lds + (bufoff) + ldsw + _i * 8192), 16, 0, 0); } while (0)
; #define PG8_LDA(dst, b, h) do { _Pragma("unroll") for (int m = 0; m < 4; ++m) _Pragma("unroll") for (int k = 0; k < 2; ++k) dst[m][k] = *(const PG8_LAS bf16x8*)(lds + PG8_SA(b, h) + aoff + m * 2048 + k * 1024); } while (0)
; #define PG8_LDB(dst, b, h) do { _Pragma("unroll") for (int n = 0; n < 2; ++n) _Pragma("unroll") for (int k = 0; k < 2; ++k) dst[n][k] = *(const PG8_LAS bf16x8*)(lds + PG8_SB(b, h) + boff + n * 2048 + k * 1024); } while (0)
; #define PG8_MMA(ai, bj, At, Bt) do { __builtin_amdgcn_s_setprio(1); _Pragma("unroll") for (int m = 0; m < 4; ++m) _Pragma("unroll") for (int n = 0; n < 2; ++n) _Pragma("unroll") for (int k = 0; k < 2; ++k) \
;         acc[ai][bj][m][n] = __builtin_amdgcn_mfma_f32_16x16x32_bf16(Bt[n][k], At[m][k], acc[ai][bj][m][n], 0, 0, 0); __builtin_amdgcn_s_setprio(0); } while (0)
; #define PG8_WAIT_V(n) asm volatile("s_waitcnt vmcnt(" #n ")" ::: "memory")
; #define PG8_WAIT_L(n) asm volatile("s_waitcnt lgkmcnt(" #n ")" ::: "memory")
; #define PG8_BAR __builtin_amdgcn_s_barrier()
; #define PG8_SCHED __builtin_amdgcn_sched_barrier(0)
; template <class Epi, class Sched, bool ALIGN_EPI = false, bool SP2 = false>
; __device__ __forceinline__ void gemm_phase(PG8_LAS unsigned char* lds, const Gemm g, const Sched& S, const Epi& E) {
;     ...
;             PG8_LDB(B0, 0, 0); PG8_LDB(B1, 0, 1); PG8_SCHED; PG8_LDA(At, 0, 0); PG8_STAGE(PG8_SA(1, 1), a1 + hstep, voffA);
;             PG8_WAIT_V(8); PG8_WAIT_L(0); PG8_BAR; PG8_MMA(0, 0, At, B0); PG8_MMA(0, 1, At, B1); PG8_BAR; PG8_SCHED;
;             PG8_LDA(At, 0, 1); PG8_STAGE(PG8_SB(0, 0), b2, voffB); PG8_STAGE(PG8_SB(0, 1), b2 + hstep, voffB); PG8_STAGE(PG8_SA(0, 0), a2, voffA);
;             PG8_WAIT_V(8); PG8_WAIT_L(0); PG8_BAR; PG8_MMA(1, 0, At, B0); PG8_MMA(1, 1, At, B1); PG8_BAR; PG8_SCHED;
.LBB0_85:
	s_add_u32 s40, s38, 0xfff80080
	s_addc_u32 s41, s39, -1
	s_add_i32 s45, 0, 0x10000
	s_cmp_eq_u32 s44, 28
	s_cselect_b32 s43, s5, s41
	s_cselect_b32 s42, s12, s40
	s_cselect_b32 s41, s23, s37
	s_cselect_b32 s40, s25, s31
	s_add_i32 s48, 0, 0x14000
	v_add_u32_e32 v140, s45, v184
	v_add_u32_e32 v154, s48, v184
	ds_read_b128 v[128:131], v140
	ds_read_b128 v[132:135], v140 offset:1024
	ds_read_b128 v[136:139], v140 offset:2048
	ds_read_b128 v[140:143], v140 offset:3072
	ds_read_b128 v[164:167], v154
	ds_read_b128 v[168:171], v154 offset:1024
	ds_read_b128 v[172:175], v154 offset:2048
	ds_read_b128 v[186:189], v154 offset:3072
	s_add_i32 m0, s58, 0xc000
	ds_read_b128 v[190:193], v185
	ds_read_b128 v[194:197], v185 offset:1024
	ds_read_b128 v[198:201], v185 offset:2048
	ds_read_b128 v[202:205], v185 offset:3072
	ds_read_b128 v[206:209], v185 offset:4096
	ds_read_b128 v[210:213], v185 offset:5120
	ds_read_b128 v[214:217], v185 offset:6144
	ds_read_b128 v[218:221], v185 offset:7168
	global_load_lds_dwordx4 v158, s[38:39]
	s_add_i32 m0, s58, 0xe000
	s_nop 0
	global_load_lds_dwordx4 v160, s[38:39]
	s_waitcnt vmcnt(8)
	s_waitcnt lgkmcnt(0)
	s_barrier
	s_setprio 1
	s_waitcnt lgkmcnt(0)
	v_mfma_f32_16x16x32_bf16 v[124:127], v[128:131], v[190:193], v[124:127]
	v_mfma_f32_16x16x32_bf16 v[124:127], v[132:135], v[194:197], v[124:127]
	v_mfma_f32_16x16x32_bf16 v[108:111], v[132:135], v[202:205], v[108:111]
	v_mfma_f32_16x16x32_bf16 v[108:111], v[128:131], v[198:201], v[108:111]
	v_mfma_f32_16x16x32_bf16 v[92:95], v[128:131], v[206:209], v[92:95]
	v_mfma_f32_16x16x32_bf16 v[92:95], v[132:135], v[210:213], v[92:95]
	v_mfma_f32_16x16x32_bf16 v[76:79], v[132:135], v[218:221], v[76:79]
	v_mfma_f32_16x16x32_bf16 v[76:79], v[128:131], v[214:217], v[76:79]
	v_mfma_f32_16x16x32_bf16 v[72:75], v[136:139], v[214:217], v[72:75]
	v_mfma_f32_16x16x32_bf16 v[72:75], v[140:143], v[218:221], v[72:75]
	v_mfma_f32_16x16x32_bf16 v[88:91], v[140:143], v[210:213], v[88:91]
	v_mfma_f32_16x16x32_bf16 v[88:91], v[136:139], v[206:209], v[88:91]
	v_mfma_f32_16x16x32_bf16 v[104:107], v[136:139], v[198:201], v[104:107]
	v_mfma_f32_16x16x32_bf16 v[104:107], v[140:143], v[202:205], v[104:107]
	v_mfma_f32_16x16x32_bf16 v[116:119], v[140:143], v[194:197], v[116:119]
	v_mfma_f32_16x16x32_bf16 v[116:119], v[136:139], v[190:193], v[116:119]
	s_setprio 0
	s_setprio 1
	v_mfma_f32_16x16x32_bf16 v[120:123], v[164:167], v[190:193], v[120:123]
	v_mfma_f32_16x16x32_bf16 v[120:123], v[168:171], v[194:197], v[120:123]
	v_mfma_f32_16x16x32_bf16 v[100:103], v[168:171], v[202:205], v[100:103]
	v_mfma_f32_16x16x32_bf16 v[100:103], v[164:167], v[198:201], v[100:103]
	v_mfma_f32_16x16x32_bf16 v[84:87], v[164:167], v[206:209], v[84:87]
	v_mfma_f32_16x16x32_bf16 v[84:87], v[168:171], v[210:213], v[84:87]
	v_mfma_f32_16x16x32_bf16 v[68:71], v[168:171], v[218:221], v[68:71]
	v_mfma_f32_16x16x32_bf16 v[68:71], v[164:167], v[214:217], v[68:71]
	v_mfma_f32_16x16x32_bf16 v[64:67], v[172:175], v[214:217], v[64:67]
	v_mfma_f32_16x16x32_bf16 v[64:67], v[186:189], v[218:221], v[64:67]
	v_mfma_f32_16x16x32_bf16 v[80:83], v[186:189], v[210:213], v[80:83]
	v_mfma_f32_16x16x32_bf16 v[80:83], v[172:175], v[206:209], v[80:83]
	v_mfma_f32_16x16x32_bf16 v[96:99], v[172:175], v[198:201], v[96:99]
	v_mfma_f32_16x16x32_bf16 v[96:99], v[186:189], v[202:205], v[96:99]
	v_mfma_f32_16x16x32_bf16 v[112:115], v[186:189], v[194:197], v[112:115]
	v_mfma_f32_16x16x32_bf16 v[112:115], v[172:175], v[190:193], v[112:115]
	s_setprio 0
	s_barrier
	s_add_i32 s45, s45, s57
	s_mov_b32 m0, s45
	ds_read_b128 v[190:193], v185 offset:16384
	ds_read_b128 v[194:197], v185 offset:17408
	ds_read_b128 v[198:201], v185 offset:18432
	ds_read_b128 v[202:205], v185 offset:19456
	ds_read_b128 v[206:209], v185 offset:20480
	ds_read_b128 v[210:213], v185 offset:21504
	ds_read_b128 v[214:217], v185 offset:22528
	ds_read_b128 v[218:221], v185 offset:23552
	global_load_lds_dwordx4 v148, s[40:41]
	s_add_i32 m0, s45, 0x2000
	s_add_u32 s46, s40, 0x80000
	s_addc_u32 s47, s41, 0
	s_add_i32 s45, s48, s57
	global_load_lds_dwordx4 v152, s[40:41]
	s_mov_b32 m0, s45
	s_nop 0
	global_load_lds_dwordx4 v148, s[46:47]
	s_add_i32 m0, s45, 0x2000
	s_nop 0
	global_load_lds_dwordx4 v152, s[46:47]
	s_mov_b32 m0, s58
	s_nop 0
	global_load_lds_dwordx4 v146, s[42:43]
	s_mov_b32 m0, s59
	s_nop 0
	global_load_lds_dwordx4 v150, s[42:43]
	s_waitcnt vmcnt(8)
	s_waitcnt lgkmcnt(0)
	s_barrier
	s_setprio 1
	s_waitcnt lgkmcnt(0)
	v_mfma_f32_16x16x32_bf16 v[60:63], v[128:131], v[190:193], v[60:63]
	v_mfma_f32_16x16x32_bf16 v[60:63], v[132:135], v[194:197], v[60:63]
	v_mfma_f32_16x16x32_bf16 v[44:47], v[132:135], v[202:205], v[44:47]
	v_mfma_f32_16x16x32_bf16 v[44:47], v[128:131], v[198:201], v[44:47]
	v_mfma_f32_16x16x32_bf16 v[28:31], v[128:131], v[206:209], v[28:31]
	v_mfma_f32_16x16x32_bf16 v[28:31], v[132:135], v[210:213], v[28:31]
	v_mfma_f32_16x16x32_bf16 v[12:15], v[132:135], v[218:221], v[12:15]
	v_mfma_f32_16x16x32_bf16 v[12:15], v[128:131], v[214:217], v[12:15]
	v_mfma_f32_16x16x32_bf16 v[8:11], v[136:139], v[214:217], v[8:11]
	v_mfma_f32_16x16x32_bf16 v[8:11], v[140:143], v[218:221], v[8:11]
	v_mfma_f32_16x16x32_bf16 v[24:27], v[140:143], v[210:213], v[24:27]
	v_mfma_f32_16x16x32_bf16 v[24:27], v[136:139], v[206:209], v[24:27]
	v_mfma_f32_16x16x32_bf16 v[40:43], v[136:139], v[198:201], v[40:43]
	v_mfma_f32_16x16x32_bf16 v[40:43], v[140:143], v[202:205], v[40:43]
	v_mfma_f32_16x16x32_bf16 v[56:59], v[140:143], v[194:197], v[56:59]
	v_mfma_f32_16x16x32_bf16 v[56:59], v[136:139], v[190:193], v[56:59]
	s_setprio 0
	s_setprio 1
	v_mfma_f32_16x16x32_bf16 v[52:55], v[164:167], v[190:193], v[52:55]
	v_mfma_f32_16x16x32_bf16 v[52:55], v[168:171], v[194:197], v[52:55]
	v_mfma_f32_16x16x32_bf16 v[36:39], v[168:171], v[202:205], v[36:39]
	v_mfma_f32_16x16x32_bf16 v[36:39], v[164:167], v[198:201], v[36:39]
	v_mfma_f32_16x16x32_bf16 v[20:23], v[164:167], v[206:209], v[20:23]
	v_mfma_f32_16x16x32_bf16 v[20:23], v[168:171], v[210:213], v[20:23]
	v_mfma_f32_16x16x32_bf16 v[4:7], v[168:171], v[218:221], v[4:7]
	v_mfma_f32_16x16x32_bf16 v[4:7], v[164:167], v[214:217], v[4:7]
	v_mfma_f32_16x16x32_bf16 v[0:3], v[172:175], v[214:217], v[0:3]
	v_mfma_f32_16x16x32_bf16 v[0:3], v[186:189], v[218:221], v[0:3]
	v_mfma_f32_16x16x32_bf16 v[16:19], v[186:189], v[210:213], v[16:19]
	v_mfma_f32_16x16x32_bf16 v[16:19], v[172:175], v[206:209], v[16:19]
	v_mfma_f32_16x16x32_bf16 v[32:35], v[172:175], v[198:201], v[32:35]
	v_mfma_f32_16x16x32_bf16 v[32:35], v[186:189], v[202:205], v[32:35]
	v_mfma_f32_16x16x32_bf16 v[48:51], v[186:189], v[194:197], v[48:51]
	v_mfma_f32_16x16x32_bf16 v[48:51], v[172:175], v[190:193], v[48:51]
	s_setprio 0
	s_barrier
; #define PG8_STAGE(bufoff, gbase, voff) do { _Pragma("unroll") for (int _i = 0; _i < 2; ++_i) \
;         __builtin_amdgcn_global_load_lds((const unsigned*)((const char*)(gbase) + (voff)[_i]), (PG8_LAS unsigned*)(lds + (bufoff) + ldsw + _i * 8192), 16, 0, 0); } while (0)
; #define PG8_LDA(dst, b, h) do { _Pragma("unroll") for (int m = 0; m < 4; ++m) _Pragma("unroll") for (int k = 0; k < 2; ++k) dst[m][k] = *(const PG8_LAS bf16x8*)(lds + PG8_SA(b, h) + aoff + m * 2048 + k * 1024); } while (0)
; #define PG8_LDB(dst, b, h) do { _Pragma("unroll") for (int n = 0; n < 2; ++n) _Pragma("unroll") for (int k = 0; k < 2; ++k) dst[n][k] = *(const PG8_LAS bf16x8*)(lds + PG8_SB(b, h) + boff + n * 2048 + k * 1024); } while (0)
; #define PG8_MMA(ai, bj, At, Bt) do { __builtin_amdgcn_s_setprio(1); _Pragma("unroll") for (int m = 0; m < 4; ++m) _Pragma("unroll") for (int n = 0; n < 2; ++n) _Pragma("unroll") for (int k = 0; k < 2; ++k) \
;         acc[ai][bj][m][n] = __builtin_amdgcn_mfma_f32_16x16x32_bf16(Bt[n][k], At[m][k], acc[ai][bj][m][n], 0, 0, 0); __builtin_amdgcn_s_setprio(0); } while (0)
; #define PG8_WAIT_V(n) asm volatile("s_waitcnt vmcnt(" #n ")" ::: "memory")
; #define PG8_WAIT_L(n) asm volatile("s_waitcnt lgkmcnt(" #n ")" ::: "memory")
; #define PG8_BAR __builtin_amdgcn_s_barrier()
; #define PG8_SCHED __builtin_amdgcn_sched_barrier(0)
; template <class Epi, class Sched, bool ALIGN_EPI = false, bool SP2 = false>
; __device__ __forceinline__ void gemm_phase(PG8_LAS unsigned char* lds, const Gemm g, const Sched& S, const Epi& E) {
;     ...
;             PG8_LDB(B0, 1, 0); PG8_LDB(B1, 1, 1); PG8_SCHED; PG8_LDA(At, 1, 0); PG8_STAGE(PG8_SA(0, 1), a2 + hstep, voffA);
;             PG8_WAIT_V(8); PG8_WAIT_L(0); PG8_BAR; PG8_MMA(0, 0, At, B0); PG8_MMA(0, 1, At, B1); PG8_BAR; PG8_SCHED;
;             PG8_LDA(At, 1, 1); PG8_STAGE(PG8_SB(1, 0), b3, voffB); PG8_STAGE(PG8_SB(1, 1), b3 + hstep, voffB); PG8_STAGE(PG8_SA(1, 0), a3, voffA);
;             PG8_WAIT_V(8); PG8_WAIT_L(0); PG8_BAR; PG8_MMA(1, 0, At, B0); PG8_MMA(1, 1, At, B1); PG8_BAR; PG8_SCHED;
	s_add_i32 s45, 0, 0x18000
	s_add_i32 s46, 0, 0x1c000
	v_add_u32_e32 v140, s45, v184
	v_add_u32_e32 v154, s46, v184
	ds_read_b128 v[128:131], v140
	ds_read_b128 v[132:135], v140 offset:1024
	ds_read_b128 v[136:139], v140 offset:2048
	ds_read_b128 v[140:143], v140 offset:3072
	ds_read_b128 v[164:167], v154
	ds_read_b128 v[168:171], v154 offset:1024
	ds_read_b128 v[172:175], v154 offset:2048
	ds_read_b128 v[186:189], v154 offset:3072
	s_add_u32 s42, s42, 0x80000
	s_addc_u32 s43, s43, 0
	s_add_u32 s100, s42, 0xfff80080
	s_addc_u32 s101, s43, -1
	s_mov_b32 m0, s60
	ds_read_b128 v[190:193], v185 offset:32768
	ds_read_b128 v[194:197], v185 offset:33792
	ds_read_b128 v[198:201], v185 offset:34816
	ds_read_b128 v[202:205], v185 offset:35840
	ds_read_b128 v[206:209], v185 offset:36864
	ds_read_b128 v[210:213], v185 offset:37888
	ds_read_b128 v[214:217], v185 offset:38912
	ds_read_b128 v[218:221], v185 offset:39936
	global_load_lds_dwordx4 v146, s[42:43]
	s_mov_b32 m0, s61
	s_nop 0
	global_load_lds_dwordx4 v150, s[42:43]
	s_waitcnt vmcnt(8)
	s_waitcnt lgkmcnt(0)
	s_barrier
	s_setprio 1
	s_waitcnt lgkmcnt(0)
	v_mfma_f32_16x16x32_bf16 v[124:127], v[128:131], v[190:193], v[124:127]
	v_mfma_f32_16x16x32_bf16 v[124:127], v[132:135], v[194:197], v[124:127]
	v_mfma_f32_16x16x32_bf16 v[108:111], v[132:135], v[202:205], v[108:111]
	v_mfma_f32_16x16x32_bf16 v[108:111], v[128:131], v[198:201], v[108:111]
	v_mfma_f32_16x16x32_bf16 v[92:95], v[128:131], v[206:209], v[92:95]
	v_mfma_f32_16x16x32_bf16 v[92:95], v[132:135], v[210:213], v[92:95]
	v_mfma_f32_16x16x32_bf16 v[76:79], v[132:135], v[218:221], v[76:79]
	v_mfma_f32_16x16x32_bf16 v[76:79], v[128:131], v[214:217], v[76:79]
	v_mfma_f32_16x16x32_bf16 v[72:75], v[136:139], v[214:217], v[72:75]
	v_mfma_f32_16x16x32_bf16 v[72:75], v[140:143], v[218:221], v[72:75]
	v_mfma_f32_16x16x32_bf16 v[88:91], v[140:143], v[210:213], v[88:91]
	v_mfma_f32_16x16x32_bf16 v[88:91], v[136:139], v[206:209], v[88:91]
	v_mfma_f32_16x16x32_bf16 v[104:107], v[136:139], v[198:201], v[104:107]
	v_mfma_f32_16x16x32_bf16 v[104:107], v[140:143], v[202:205], v[104:107]
	v_mfma_f32_16x16x32_bf16 v[116:119], v[140:143], v[194:197], v[116:119]
	v_mfma_f32_16x16x32_bf16 v[116:119], v[136:139], v[190:193], v[116:119]
	s_setprio 0
	s_setprio 1
	v_mfma_f32_16x16x32_bf16 v[120:123], v[164:167], v[190:193], v[120:123]
	v_mfma_f32_16x16x32_bf16 v[120:123], v[168:171], v[194:197], v[120:123]
	v_mfma_f32_16x16x32_bf16 v[100:103], v[168:171], v[202:205], v[100:103]
	v_mfma_f32_16x16x32_bf16 v[100:103], v[164:167], v[198:201], v[100:103]
	v_mfma_f32_16x16x32_bf16 v[84:87], v[164:167], v[206:209], v[84:87]
	v_mfma_f32_16x16x32_bf16 v[84:87], v[168:171], v[210:213], v[84:87]
	v_mfma_f32_16x16x32_bf16 v[68:71], v[168:171], v[218:221], v[68:71]
	v_mfma_f32_16x16x32_bf16 v[68:71], v[164:167], v[214:217], v[68:71]
	v_mfma_f32_16x16x32_bf16 v[64:67], v[172:175], v[214:217], v[64:67]
	v_mfma_f32_16x16x32_bf16 v[64:67], v[186:189], v[218:221], v[64:67]
	v_mfma_f32_16x16x32_bf16 v[80:83], v[186:189], v[210:213], v[80:83]
	v_mfma_f32_16x16x32_bf16 v[80:83], v[172:175], v[206:209], v[80:83]
	v_mfma_f32_16x16x32_bf16 v[96:99], v[172:175], v[198:201], v[96:99]
	v_mfma_f32_16x16x32_bf16 v[96:99], v[186:189], v[202:205], v[96:99]
	v_mfma_f32_16x16x32_bf16 v[112:115], v[186:189], v[194:197], v[112:115]
	v_mfma_f32_16x16x32_bf16 v[112:115], v[172:175], v[190:193], v[112:115]
	s_setprio 0
	s_barrier
	s_add_i32 s42, s45, s57
	s_add_u32 s40, s40, 0x80
	s_addc_u32 s41, s41, 0
	s_mov_b32 m0, s42
	ds_read_b128 v[190:193], v185 offset:49152
	ds_read_b128 v[194:197], v185 offset:50176
	ds_read_b128 v[198:201], v185 offset:51200
	ds_read_b128 v[202:205], v185 offset:52224
	ds_read_b128 v[206:209], v185 offset:53248
	ds_read_b128 v[210:213], v185 offset:54272
	ds_read_b128 v[214:217], v185 offset:55296
	ds_read_b128 v[218:221], v185 offset:56320
	global_load_lds_dwordx4 v148, s[40:41]
	s_add_i32 m0, s42, 0x2000
	s_add_i32 s42, s46, s57
	global_load_lds_dwordx4 v152, s[40:41]
	s_add_u32 s40, s40, 0x80000
	s_addc_u32 s41, s41, 0
	s_mov_b32 m0, s42
	s_nop 0
	global_load_lds_dwordx4 v148, s[40:41]
	s_add_i32 m0, s42, 0x2000
	s_nop 0
	global_load_lds_dwordx4 v152, s[40:41]
	s_mov_b32 m0, s63
	s_nop 0
	global_load_lds_dwordx4 v146, s[100:101]
	s_mov_b32 m0, s64
	s_nop 0
	global_load_lds_dwordx4 v150, s[100:101]
	s_waitcnt vmcnt(8)
	s_waitcnt lgkmcnt(0)
	s_barrier
	s_setprio 1
	s_waitcnt lgkmcnt(0)
	v_mfma_f32_16x16x32_bf16 v[60:63], v[128:131], v[190:193], v[60:63]
	v_mfma_f32_16x16x32_bf16 v[60:63], v[132:135], v[194:197], v[60:63]
	v_mfma_f32_16x16x32_bf16 v[44:47], v[132:135], v[202:205], v[44:47]
	v_mfma_f32_16x16x32_bf16 v[44:47], v[128:131], v[198:201], v[44:47]
	v_mfma_f32_16x16x32_bf16 v[28:31], v[128:131], v[206:209], v[28:31]
	v_mfma_f32_16x16x32_bf16 v[28:31], v[132:135], v[210:213], v[28:31]
	v_mfma_f32_16x16x32_bf16 v[12:15], v[132:135], v[218:221], v[12:15]
	v_mfma_f32_16x16x32_bf16 v[12:15], v[128:131], v[214:217], v[12:15]
	v_mfma_f32_16x16x32_bf16 v[8:11], v[136:139], v[214:217], v[8:11]
	v_mfma_f32_16x16x32_bf16 v[8:11], v[140:143], v[218:221], v[8:11]
	v_mfma_f32_16x16x32_bf16 v[24:27], v[140:143], v[210:213], v[24:27]
	v_mfma_f32_16x16x32_bf16 v[24:27], v[136:139], v[206:209], v[24:27]
	v_mfma_f32_16x16x32_bf16 v[40:43], v[136:139], v[198:201], v[40:43]
	v_mfma_f32_16x16x32_bf16 v[40:43], v[140:143], v[202:205], v[40:43]
	v_mfma_f32_16x16x32_bf16 v[56:59], v[140:143], v[194:197], v[56:59]
	v_mfma_f32_16x16x32_bf16 v[56:59], v[136:139], v[190:193], v[56:59]
	s_setprio 0
	s_setprio 1
	v_mfma_f32_16x16x32_bf16 v[52:55], v[164:167], v[190:193], v[52:55]
	v_mfma_f32_16x16x32_bf16 v[52:55], v[168:171], v[194:197], v[52:55]
	v_mfma_f32_16x16x32_bf16 v[36:39], v[168:171], v[202:205], v[36:39]
	v_mfma_f32_16x16x32_bf16 v[36:39], v[164:167], v[198:201], v[36:39]
	v_mfma_f32_16x16x32_bf16 v[20:23], v[164:167], v[206:209], v[20:23]
	v_mfma_f32_16x16x32_bf16 v[20:23], v[168:171], v[210:213], v[20:23]
	v_mfma_f32_16x16x32_bf16 v[4:7], v[168:171], v[218:221], v[4:7]
	v_mfma_f32_16x16x32_bf16 v[4:7], v[164:167], v[214:217], v[4:7]
	v_mfma_f32_16x16x32_bf16 v[0:3], v[172:175], v[214:217], v[0:3]
	v_mfma_f32_16x16x32_bf16 v[0:3], v[186:189], v[218:221], v[0:3]
	v_mfma_f32_16x16x32_bf16 v[16:19], v[186:189], v[210:213], v[16:19]
	v_mfma_f32_16x16x32_bf16 v[16:19], v[172:175], v[206:209], v[16:19]
	v_mfma_f32_16x16x32_bf16 v[32:35], v[172:175], v[198:201], v[32:35]
	v_mfma_f32_16x16x32_bf16 v[32:35], v[186:189], v[202:205], v[32:35]
	v_mfma_f32_16x16x32_bf16 v[48:51], v[186:189], v[194:197], v[48:51]
	v_mfma_f32_16x16x32_bf16 v[48:51], v[172:175], v[190:193], v[48:51]
	s_setprio 0
	s_barrier
	s_add_i32 s44, s44, 2
	s_add_u32 s38, s38, 0x100
	s_addc_u32 s39, s39, 0
	s_add_u32 s31, s31, 0x100
	s_addc_u32 s37, s37, 0
	s_cmp_gt_u32 s44, 29
	s_cbranch_scc0 .LBB0_85
	s_and_b64 vcc, exec, s[20:21]
	s_cbranch_vccz .LBB0_88
	s_barrier
